# S6 plus attention epilogue gate loads widened: 16 dwordx2 per lane to 8 dwordx4 with v_permlane32_swap (same bytes)
# speedup vs baseline: 1.0128x; 1.0090x over previous
; __device__ __forceinline__ unsigned cvt_pk_bf16(float lo, float hi) { unsigned r; asm volatile("v_cvt_pk_bf16_f32 %0, %1, %2" : "=v"(r) : "v"(lo), "v"(hi)); return r; }
; __device__ __forceinline__ float bf_lo(unsigned w) { return __uint_as_float(w << 16); }
; __device__ __forceinline__ float bf_hi(unsigned w) { return __uint_as_float(w & 0xffff0000u); }
; #define ATT_LOADK(t) do { rk0 = *(const u32x4*)(gk + (size_t)(64 * (t)) * NKN); rk1 = *(const u32x4*)(gk + (size_t)(64 * (t) + 32) * NKN); rr = *(const u32x4*)(gr + (size_t)(64 * (t)) * 64); } while (0)
; #define ATT_LOADV(t) do { rv0 = *(const u32x4*)(gv + 64 * (t)); rv1 = *(const u32x4*)(gv + (size_t)64 * M + 64 * (t)); } while (0)
; #define ATT_STOREK(ko) do { *(LAS u32x4*)(lds + (ko) + lk) = rk0; *(LAS u32x4*)(lds + (ko) + lk + 32 * KROW) = rk1; *(LAS u32x4*)(lds + (ko) + lr) = rr; } while (0)
; __device__ __forceinline__ void unit(LAS unsigned char* lds, int b, int h, int qb, const bf16_t* Q, const bf16_t* Kn, const bf16_t* Kr, const bf16_t* VT, const bf16_t* proj, bf16_t* ymix, int wv) {
;     ...
;     ATT_LOADK(0); ATT_LOADV(0); ATT_STOREK(0); ATT_STOREV(0);
;     ATT_LOADK(1); ATT_STOREK(KBUF);
;     __syncthreads();
; #pragma unroll
;     for (int ks = 0; ks < 12; ++ks) asm volatile("" : "+v"(qf[ks]));
;     int k0 = 0, k1 = KBUF, k2 = 2 * KBUF, v0 = 0, v1 = VBUF;
;     ...
;     lrun += shfl_xor_f(lrun, 32);
;     const float inv = 1.f / lrun;
;     const size_t tok = (size_t)tok0 + qidx;
;     u32x2 gts[4][4];
; #pragma unroll
;     for (int blk = 0; blk < 4; ++blk)
; #pragma unroll
;         for (int g = 0; g < 4; ++g) gts[blk][g] = *(const u32x2*)(proj + tok * NIN + PJ_BG + h * 128 + 32 * blk + 8 * g + 4 * hi);
; #pragma unroll
;     for (int blk = 0; blk < 4; ++blk)
; #pragma unroll
;         for (int g = 0; g < 4; ++g) { const int dv = 32 * blk + 8 * g + 4 * hi; const u32x2 gt = gts[blk][g];
;             u32x2 w; w.x = cvt_pk_bf16(o[blk][4 * g + 0] * inv * bf_lo(gt.x), o[blk][4 * g + 1] * inv * bf_hi(gt.x)); w.y = cvt_pk_bf16(o[blk][4 * g + 2] * inv * bf_lo(gt.y), o[blk][4 * g + 3] * inv * bf_hi(gt.y));
;             *(u32x2*)(ymix + tok * DM + 512 + h * 128 + dv) = w; }
.LBB0_605:
	s_add_i32 s8, s71, 0
	s_add_i32 s8, s8, 0x12c00
	v_add3_u32 v0, s8, v227, v226
	ds_read2_b64 v[2:5], v0 offset1:2
	v_ashrrev_i32_e32 v217, 31, v216
	v_mov_b64_e32 v[6:7], s[22:23]
	v_lshl_add_u64 v[120:121], v[216:217], 0, s[54:55]
	v_mad_u64_u32 v[122:123], s[8:9], v120, s66, v[6:7]
	ds_read2_b64 v[6:9], v0 offset0:4 offset1:6
	ds_read2_b64 v[12:15], v0 offset0:8 offset1:10
	v_add_u32_e32 v88, 0x1000, v0
	v_add_u32_e32 v104, 0x2000, v0
	s_waitcnt lgkmcnt(2)
	v_mfma_f32_32x32x16_bf16 v[64:79], v[2:5], v[200:203], v[64:79]
	ds_read2_b64 v[2:5], v0 offset0:12 offset1:14
	v_add_u32_e32 v0, 0x3000, v0
	v_mad_i32_i24 v123, v121, s66, v123
	s_lshl_b32 s12, s69, 1
	ds_read2_b64 v[80:83], v88 offset0:32 offset1:34
	ds_read2_b64 v[84:87], v88 offset0:36 offset1:38
	v_mov_b32_e32 v11, v222
	s_add_i32 s68, s68, s31
	s_waitcnt lgkmcnt(4)
	v_mfma_f32_32x32x16_bf16 v[64:79], v[6:9], v[196:199], v[64:79]
	ds_read2_b64 v[6:9], v88 offset0:40 offset1:42
	ds_read2_b64 v[88:91], v88 offset0:44 offset1:46
	ds_read2_b64 v[92:95], v104 offset0:64 offset1:66
	ds_read2_b64 v[96:99], v104 offset0:68 offset1:70
	ds_read2_b64 v[100:103], v104 offset0:72 offset1:74
	ds_read2_b64 v[104:107], v104 offset0:76 offset1:78
	ds_read2_b64 v[108:111], v0 offset0:96 offset1:98
	s_cmpk_lt_i32 s68, 0x400
	s_waitcnt lgkmcnt(10)
	v_mfma_f32_32x32x16_bf16 v[64:79], v[12:15], v[192:195], v[64:79]
	ds_read2_b64 v[12:15], v0 offset0:100 offset1:102
	ds_read2_b64 v[112:115], v0 offset0:104 offset1:106
	ds_read2_b64 v[116:119], v0 offset0:108 offset1:110
	v_lshlrev_b32_e32 v0, 1, v225
	s_waitcnt lgkmcnt(0)
	s_barrier
	v_mfma_f32_32x32x16_bf16 v[64:79], v[2:5], v[180:183], v[64:79]
	v_lshl_add_u64 v[2:3], v[122:123], 0, s[12:13]
	v_lshl_add_u64 v[2:3], v[2:3], 0, v[0:1]
	v_add_co_u32_e32 v4, vcc, s67, v2
	s_nop 1
	v_addc_co_u32_e32 v5, vcc, 0, v3, vcc
	v_and_b32_e32 v168, 32, v222
	v_lshrrev_b32_e32 v168, 2, v168
	v_mov_b32_e32 v169, 0
	v_lshl_add_u64 v[168:169], v[4:5], 0, v[168:169]
	global_load_dwordx4 v[136:139], v[168:169], off
	v_lshl_add_u64 v[2:3], v[2:3], 0, s[16:17]
	v_mfma_f32_32x32x16_bf16 v[48:63], v[80:83], v[200:203], v[48:63]
	global_load_dwordx4 v[140:143], v[168:169], off offset:32
	v_lshlrev_b32_e32 v4, 2, v11
	v_xor_b32_e32 v4, 0x80, v4
	ds_bpermute_b32 v4, v4, v10
	v_mfma_f32_32x32x16_bf16 v[48:63], v[84:87], v[196:199], v[48:63]
	v_mfma_f32_32x32x16_bf16 v[48:63], v[6:9], v[192:195], v[48:63]
	s_waitcnt lgkmcnt(0)
	v_add_f32_e32 v6, v10, v4
	global_load_dwordx4 v[144:147], v[168:169], off offset:64
	global_load_dwordx4 v[148:151], v[168:169], off offset:96
	global_load_dwordx4 v[152:155], v[168:169], off offset:128
	v_div_scale_f32 v7, s[8:9], v6, v6, 1.0
	v_rcp_f32_e32 v134, v7
	v_mfma_f32_32x32x16_bf16 v[48:63], v[88:91], v[180:183], v[48:63]
	global_load_dwordx4 v[156:159], v[168:169], off offset:160
	global_load_dwordx4 v[160:163], v[168:169], off offset:192
	global_load_dwordx4 v[164:167], v[168:169], off offset:224
	s_nop 0
	v_mfma_f32_32x32x16_bf16 v[32:47], v[92:95], v[200:203], v[32:47]
	v_fma_f32 v92, -v7, v134, 1.0
	v_fmac_f32_e32 v134, v92, v134
	v_div_scale_f32 v92, vcc, 1.0, v6, 1.0
	v_mul_f32_e32 v93, v92, v134
	v_fma_f32 v94, -v7, v93, v92
	v_fmac_f32_e32 v93, v94, v134
	v_fma_f32 v7, -v7, v93, v92
	v_mfma_f32_32x32x16_bf16 v[16:31], v[108:111], v[200:203], v[16:31]
	v_div_fmas_f32 v7, v7, v134, v93
	v_div_fixup_f32 v92, v7, v6, 1.0
	v_mul_f32_e32 v64, v64, v92
	v_lshlrev_b64 v[6:7], 12, v[120:121]
	v_mul_f32_e32 v65, v65, v92
	v_lshl_add_u64 v[6:7], s[46:47], 0, v[6:7]
	v_lshl_add_u64 v[6:7], v[6:7], 0, s[12:13]
	v_lshl_add_u64 v[6:7], v[6:7], 0, v[0:1]
	v_mul_f32_e32 v0, v68, v92
	v_mfma_f32_32x32x16_bf16 v[16:31], v[12:15], v[196:199], v[16:31]
	v_mul_f32_e32 v12, v69, v92
	s_waitcnt vmcnt(7)
	v_permlane32_swap_b32_e32 v136, v138
	v_permlane32_swap_b32_e32 v137, v139
	v_lshlrev_b32_e32 v93, 16, v136
	v_mul_f32_e32 v64, v64, v93
	v_and_b32_e32 v93, 0xffff0000, v136
	v_mul_f32_e32 v65, v65, v93
	v_cvt_pk_bf16_f32 v244, v64, v65
	v_mul_f32_e32 v65, v66, v92
	v_lshlrev_b32_e32 v66, 16, v137
	v_mul_f32_e32 v65, v65, v66
	v_mul_f32_e32 v66, v67, v92
	v_and_b32_e32 v67, 0xffff0000, v137
	v_mul_f32_e32 v66, v66, v67
	v_cvt_pk_bf16_f32 v245, v65, v66
	v_and_b32_e32 v252, 32, v222
	v_lshrrev_b32_e32 v252, 2, v252
	v_mov_b32_e32 v253, 0
	v_lshl_add_u64 v[252:253], v[6:7], 0, v[252:253]
	s_waitcnt vmcnt(7)
	v_lshlrev_b32_e32 v64, 16, v138
	v_and_b32_e32 v13, 0xffff0000, v138
	v_mul_f32_e32 v0, v0, v64
	v_mul_f32_e32 v12, v12, v13
	v_cvt_pk_bf16_f32 v246, v0, v12
	v_mul_f32_e32 v0, v70, v92
	v_lshlrev_b32_e32 v13, 16, v139
	v_mul_f32_e32 v0, v0, v13
	v_mul_f32_e32 v13, v71, v92
	v_and_b32_e32 v14, 0xffff0000, v139
	v_mul_f32_e32 v13, v13, v14
	v_cvt_pk_bf16_f32 v247, v0, v13
	s_nop 1
	v_permlane32_swap_b32_e32 v244, v246
	v_permlane32_swap_b32_e32 v245, v247
	global_store_dwordx4 v[252:253], v[244:247], off offset:1024
	v_mul_f32_e32 v0, v72, v92
	s_waitcnt vmcnt(7)
	v_permlane32_swap_b32_e32 v140, v142
	v_permlane32_swap_b32_e32 v141, v143
	v_lshlrev_b32_e32 v12, 16, v140
	v_mul_f32_e32 v0, v0, v12
	v_mul_f32_e32 v12, v73, v92
	v_and_b32_e32 v13, 0xffff0000, v140
	v_mul_f32_e32 v12, v12, v13
	v_cvt_pk_bf16_f32 v248, v0, v12
	v_mul_f32_e32 v0, v74, v92
	v_lshlrev_b32_e32 v13, 16, v141
	v_mul_f32_e32 v0, v0, v13
	v_mul_f32_e32 v13, v75, v92
	v_and_b32_e32 v14, 0xffff0000, v141
	v_mul_f32_e32 v13, v13, v14
	v_cvt_pk_bf16_f32 v249, v0, v13
	v_mul_f32_e32 v0, v76, v92
	s_waitcnt vmcnt(7)
; __device__ __forceinline__ unsigned cvt_pk_bf16(float lo, float hi) { unsigned r; asm volatile("v_cvt_pk_bf16_f32 %0, %1, %2" : "=v"(r) : "v"(lo), "v"(hi)); return r; }
; __device__ __forceinline__ float bf_lo(unsigned w) { return __uint_as_float(w << 16); }
; __device__ __forceinline__ float bf_hi(unsigned w) { return __uint_as_float(w & 0xffff0000u); }
; __device__ __forceinline__ void unit(LAS unsigned char* lds, int b, int h, int qb, const bf16_t* Q, const bf16_t* Kn, const bf16_t* Kr, const bf16_t* VT, const bf16_t* proj, bf16_t* ymix, int wv) {
;     ...
;     u32x2 gts[4][4];
; #pragma unroll
;     for (int blk = 0; blk < 4; ++blk)
; #pragma unroll
;         for (int g = 0; g < 4; ++g) gts[blk][g] = *(const u32x2*)(proj + tok * NIN + PJ_BG + h * 128 + 32 * blk + 8 * g + 4 * hi);
; #pragma unroll
;     for (int blk = 0; blk < 4; ++blk)
; #pragma unroll
;         for (int g = 0; g < 4; ++g) { const int dv = 32 * blk + 8 * g + 4 * hi; const u32x2 gt = gts[blk][g];
;             u32x2 w; w.x = cvt_pk_bf16(o[blk][4 * g + 0] * inv * bf_lo(gt.x), o[blk][4 * g + 1] * inv * bf_hi(gt.x)); w.y = cvt_pk_bf16(o[blk][4 * g + 2] * inv * bf_lo(gt.y), o[blk][4 * g + 3] * inv * bf_hi(gt.y));
;             *(u32x2*)(ymix + tok * DM + 512 + h * 128 + dv) = w; }
	v_lshlrev_b32_e32 v12, 16, v142
	v_mul_f32_e32 v0, v0, v12
	v_mul_f32_e32 v12, v77, v92
	v_and_b32_e32 v10, 0xffff0000, v142
	v_mul_f32_e32 v10, v12, v10
	v_cvt_pk_bf16_f32 v250, v0, v10
	v_mul_f32_e32 v0, v78, v92
	v_lshlrev_b32_e32 v12, 16, v143
	v_mul_f32_e32 v0, v0, v12
	v_mul_f32_e32 v12, v79, v92
	v_and_b32_e32 v11, 0xffff0000, v143
	v_mul_f32_e32 v11, v12, v11
	v_mfma_f32_32x32x16_bf16 v[32:47], v[96:99], v[196:199], v[32:47]
	v_cvt_pk_bf16_f32 v251, v0, v11
	s_nop 1
	v_permlane32_swap_b32_e32 v248, v250
	v_permlane32_swap_b32_e32 v249, v251
	global_store_dwordx4 v[252:253], v[248:251], off offset:1056
	v_mul_f32_e32 v0, v48, v92
	s_waitcnt vmcnt(7)
	v_permlane32_swap_b32_e32 v144, v146
	v_permlane32_swap_b32_e32 v145, v147
	v_lshlrev_b32_e32 v10, 16, v144
	v_mul_f32_e32 v0, v0, v10
	v_mul_f32_e32 v10, v49, v92
	v_and_b32_e32 v11, 0xffff0000, v144
	v_mul_f32_e32 v10, v10, v11
	v_cvt_pk_bf16_f32 v244, v0, v10
	v_mul_f32_e32 v0, v50, v92
	v_lshlrev_b32_e32 v11, 16, v145
	v_mul_f32_e32 v0, v0, v11
	v_mul_f32_e32 v11, v51, v92
	v_and_b32_e32 v12, 0xffff0000, v145
	v_mul_f32_e32 v11, v11, v12
	v_cvt_pk_bf16_f32 v245, v0, v11
	v_mul_f32_e32 v0, v52, v92
	s_waitcnt vmcnt(7)
	v_lshlrev_b32_e32 v10, 16, v146
	v_mul_f32_e32 v0, v0, v10
	v_mul_f32_e32 v10, v53, v92
	v_and_b32_e32 v11, 0xffff0000, v146
	v_mfma_f32_32x32x16_bf16 v[32:47], v[100:103], v[192:195], v[32:47]
	v_mul_f32_e32 v10, v10, v11
	v_cvt_pk_bf16_f32 v246, v0, v10
	v_mul_f32_e32 v0, v54, v92
	v_lshlrev_b32_e32 v11, 16, v147
	v_mul_f32_e32 v0, v0, v11
	v_mul_f32_e32 v11, v55, v92
	v_and_b32_e32 v12, 0xffff0000, v147
	v_mul_f32_e32 v11, v11, v12
	v_cvt_pk_bf16_f32 v247, v0, v11
	s_nop 1
	v_permlane32_swap_b32_e32 v244, v246
	v_permlane32_swap_b32_e32 v245, v247
	global_store_dwordx4 v[252:253], v[244:247], off offset:1088
	v_mul_f32_e32 v0, v56, v92
	s_waitcnt vmcnt(7)
	v_permlane32_swap_b32_e32 v148, v150
	v_permlane32_swap_b32_e32 v149, v151
	v_lshlrev_b32_e32 v10, 16, v148
	v_mul_f32_e32 v0, v0, v10
	v_mul_f32_e32 v10, v57, v92
	v_and_b32_e32 v11, 0xffff0000, v148
	v_mul_f32_e32 v10, v10, v11
	v_cvt_pk_bf16_f32 v248, v0, v10
	v_mul_f32_e32 v0, v58, v92
	v_lshlrev_b32_e32 v11, 16, v149
	v_mfma_f32_32x32x16_bf16 v[32:47], v[104:107], v[180:183], v[32:47]
	v_mul_f32_e32 v0, v0, v11
	v_mul_f32_e32 v11, v59, v92
	v_and_b32_e32 v12, 0xffff0000, v149
	v_mul_f32_e32 v11, v11, v12
	v_cvt_pk_bf16_f32 v249, v0, v11
	v_mul_f32_e32 v0, v60, v92
	s_waitcnt vmcnt(7)
	v_lshlrev_b32_e32 v10, 16, v150
	v_mul_f32_e32 v0, v0, v10
	v_mul_f32_e32 v10, v61, v92
	v_and_b32_e32 v11, 0xffff0000, v150
	v_mul_f32_e32 v10, v10, v11
	v_cvt_pk_bf16_f32 v250, v0, v10
	v_mul_f32_e32 v0, v62, v92
	v_lshlrev_b32_e32 v11, 16, v151
	v_mul_f32_e32 v0, v0, v11
	v_mul_f32_e32 v11, v63, v92
	v_and_b32_e32 v12, 0xffff0000, v151
	v_mul_f32_e32 v11, v11, v12
	v_cvt_pk_bf16_f32 v251, v0, v11
	s_nop 1
	v_permlane32_swap_b32_e32 v248, v250
	v_permlane32_swap_b32_e32 v249, v251
	global_store_dwordx4 v[252:253], v[248:251], off offset:1120
	v_mul_f32_e32 v0, v32, v92
	s_waitcnt vmcnt(7)
	v_permlane32_swap_b32_e32 v152, v154
	v_permlane32_swap_b32_e32 v153, v155
	v_lshlrev_b32_e32 v10, 16, v152
	v_mul_f32_e32 v0, v0, v10
	v_mul_f32_e32 v10, v33, v92
	v_and_b32_e32 v11, 0xffff0000, v152
	v_mul_f32_e32 v10, v10, v11
	v_cvt_pk_bf16_f32 v244, v0, v10
	v_mul_f32_e32 v0, v34, v92
	v_lshlrev_b32_e32 v11, 16, v153
	v_mul_f32_e32 v0, v0, v11
	v_mul_f32_e32 v11, v35, v92
	v_and_b32_e32 v12, 0xffff0000, v153
	v_mul_f32_e32 v11, v11, v12
	v_cvt_pk_bf16_f32 v245, v0, v11
	v_mul_f32_e32 v0, v36, v92
	s_waitcnt vmcnt(7)
; __device__ __forceinline__ unsigned cvt_pk_bf16(float lo, float hi) { unsigned r; asm volatile("v_cvt_pk_bf16_f32 %0, %1, %2" : "=v"(r) : "v"(lo), "v"(hi)); return r; }
; __device__ __forceinline__ float bf_lo(unsigned w) { return __uint_as_float(w << 16); }
; __device__ __forceinline__ float bf_hi(unsigned w) { return __uint_as_float(w & 0xffff0000u); }
; __device__ __forceinline__ void unit(LAS unsigned char* lds, int b, int h, int qb, const bf16_t* Q, const bf16_t* Kn, const bf16_t* Kr, const bf16_t* VT, const bf16_t* proj, bf16_t* ymix, int wv) {
;     ...
;     u32x2 gts[4][4];
; #pragma unroll
;     for (int blk = 0; blk < 4; ++blk)
; #pragma unroll
;         for (int g = 0; g < 4; ++g) gts[blk][g] = *(const u32x2*)(proj + tok * NIN + PJ_BG + h * 128 + 32 * blk + 8 * g + 4 * hi);
; #pragma unroll
;     for (int blk = 0; blk < 4; ++blk)
; #pragma unroll
;         for (int g = 0; g < 4; ++g) { const int dv = 32 * blk + 8 * g + 4 * hi; const u32x2 gt = gts[blk][g];
;             u32x2 w; w.x = cvt_pk_bf16(o[blk][4 * g + 0] * inv * bf_lo(gt.x), o[blk][4 * g + 1] * inv * bf_hi(gt.x)); w.y = cvt_pk_bf16(o[blk][4 * g + 2] * inv * bf_lo(gt.y), o[blk][4 * g + 3] * inv * bf_hi(gt.y));
;             *(u32x2*)(ymix + tok * DM + 512 + h * 128 + dv) = w; }
	v_lshlrev_b32_e32 v10, 16, v154
	v_mul_f32_e32 v0, v0, v10
	v_mul_f32_e32 v10, v37, v92
	v_and_b32_e32 v11, 0xffff0000, v154
	v_mfma_f32_32x32x16_bf16 v[16:31], v[112:115], v[192:195], v[16:31]
	v_mul_f32_e32 v10, v10, v11
	v_cvt_pk_bf16_f32 v246, v0, v10
	v_mul_f32_e32 v0, v38, v92
	v_lshlrev_b32_e32 v11, 16, v155
	v_mul_f32_e32 v0, v0, v11
	v_mul_f32_e32 v11, v39, v92
	v_and_b32_e32 v12, 0xffff0000, v155
	v_mul_f32_e32 v11, v11, v12
	v_cvt_pk_bf16_f32 v247, v0, v11
	s_nop 1
	v_permlane32_swap_b32_e32 v244, v246
	v_permlane32_swap_b32_e32 v245, v247
	global_store_dwordx4 v[252:253], v[244:247], off offset:1152
	v_mul_f32_e32 v0, v40, v92
	s_waitcnt vmcnt(7)
	v_permlane32_swap_b32_e32 v156, v158
	v_permlane32_swap_b32_e32 v157, v159
	v_lshlrev_b32_e32 v10, 16, v156
	v_mul_f32_e32 v0, v0, v10
	v_mul_f32_e32 v10, v41, v92
	v_and_b32_e32 v11, 0xffff0000, v156
	v_mul_f32_e32 v10, v10, v11
	v_cvt_pk_bf16_f32 v248, v0, v10
	v_mul_f32_e32 v0, v42, v92
	v_lshlrev_b32_e32 v11, 16, v157
	v_mfma_f32_32x32x16_bf16 v[16:31], v[116:119], v[180:183], v[16:31]
	v_mul_f32_e32 v0, v0, v11
	v_mul_f32_e32 v11, v43, v92
	v_and_b32_e32 v12, 0xffff0000, v157
	v_mul_f32_e32 v11, v11, v12
	v_cvt_pk_bf16_f32 v249, v0, v11
	v_mul_f32_e32 v0, v44, v92
	s_waitcnt vmcnt(7)
	v_lshlrev_b32_e32 v10, 16, v158
	v_mul_f32_e32 v0, v0, v10
	v_mul_f32_e32 v10, v45, v92
	v_and_b32_e32 v11, 0xffff0000, v158
	v_mul_f32_e32 v10, v10, v11
	v_cvt_pk_bf16_f32 v250, v0, v10
	v_mul_f32_e32 v0, v46, v92
	v_lshlrev_b32_e32 v11, 16, v159
	v_mul_f32_e32 v0, v0, v11
	v_mul_f32_e32 v11, v47, v92
	v_and_b32_e32 v12, 0xffff0000, v159
	v_mul_f32_e32 v11, v11, v12
	v_cvt_pk_bf16_f32 v251, v0, v11
	s_nop 1
	v_permlane32_swap_b32_e32 v248, v250
	v_permlane32_swap_b32_e32 v249, v251
	global_store_dwordx4 v[252:253], v[248:251], off offset:1184
	v_mul_f32_e32 v0, v16, v92
	s_waitcnt vmcnt(7)
	v_permlane32_swap_b32_e32 v160, v162
	v_permlane32_swap_b32_e32 v161, v163
	v_lshlrev_b32_e32 v10, 16, v160
	v_mul_f32_e32 v0, v0, v10
	v_mul_f32_e32 v10, v17, v92
	v_and_b32_e32 v11, 0xffff0000, v160
	v_mul_f32_e32 v10, v10, v11
	v_cvt_pk_bf16_f32 v244, v0, v10
	v_mul_f32_e32 v0, v18, v92
	v_lshlrev_b32_e32 v11, 16, v161
	v_mul_f32_e32 v0, v0, v11
	v_mul_f32_e32 v11, v19, v92
	v_and_b32_e32 v12, 0xffff0000, v161
	v_mul_f32_e32 v11, v11, v12
	v_cvt_pk_bf16_f32 v245, v0, v11
	v_mul_f32_e32 v0, v20, v92
	s_waitcnt vmcnt(7)
	v_lshlrev_b32_e32 v10, 16, v162
	v_mul_f32_e32 v0, v0, v10
	v_mul_f32_e32 v10, v21, v92
	v_and_b32_e32 v8, 0xffff0000, v162
	v_mul_f32_e32 v8, v10, v8
	v_cvt_pk_bf16_f32 v246, v0, v8
	v_mul_f32_e32 v0, v22, v92
	v_lshlrev_b32_e32 v10, 16, v163
	v_mul_f32_e32 v0, v0, v10
	v_mul_f32_e32 v10, v23, v92
	v_and_b32_e32 v9, 0xffff0000, v163
	v_mul_f32_e32 v9, v10, v9
	v_cvt_pk_bf16_f32 v247, v0, v9
	s_nop 1
	v_permlane32_swap_b32_e32 v244, v246
	v_permlane32_swap_b32_e32 v245, v247
	global_store_dwordx4 v[252:253], v[244:247], off offset:1216
	v_mul_f32_e32 v0, v24, v92
	s_waitcnt vmcnt(7)
	v_permlane32_swap_b32_e32 v164, v166
	v_permlane32_swap_b32_e32 v165, v167
	v_lshlrev_b32_e32 v8, 16, v164
	v_mul_f32_e32 v0, v0, v8
	v_mul_f32_e32 v8, v25, v92
	v_and_b32_e32 v4, 0xffff0000, v164
	v_mul_f32_e32 v4, v8, v4
	v_cvt_pk_bf16_f32 v248, v0, v4
	v_mul_f32_e32 v0, v26, v92
	v_lshlrev_b32_e32 v8, 16, v165
	v_mul_f32_e32 v0, v0, v8
	v_mul_f32_e32 v8, v27, v92
	v_and_b32_e32 v5, 0xffff0000, v165
	v_mul_f32_e32 v5, v8, v5
	v_cvt_pk_bf16_f32 v249, v0, v5
	v_mul_f32_e32 v0, v28, v92
	s_waitcnt vmcnt(7)
	v_lshlrev_b32_e32 v4, 16, v166
	v_mul_f32_e32 v0, v0, v4
	v_mul_f32_e32 v4, v29, v92
	v_and_b32_e32 v2, 0xffff0000, v166
	v_mul_f32_e32 v2, v4, v2
	v_cvt_pk_bf16_f32 v250, v0, v2
	v_mul_f32_e32 v0, v30, v92
	v_lshlrev_b32_e32 v4, 16, v167
	v_mul_f32_e32 v0, v0, v4
	v_mul_f32_e32 v4, v31, v92
	v_and_b32_e32 v3, 0xffff0000, v167
	v_mul_f32_e32 v3, v4, v3
	v_cvt_pk_bf16_f32 v251, v0, v3
	s_nop 1
	v_permlane32_swap_b32_e32 v248, v250
	v_permlane32_swap_b32_e32 v249, v251
	global_store_dwordx4 v[252:253], v[248:251], off offset:1248
	s_cbranch_scc0 .LBB0_633

; __device__ __forceinline__ unsigned cvt_pk_bf16(float lo, float hi) { unsigned r; asm volatile("v_cvt_pk_bf16_f32 %0, %1, %2" : "=v"(r) : "v"(lo), "v"(hi)); return r; }
; __device__ __forceinline__ float bf_lo(unsigned w) { return __uint_as_float(w << 16); }
; __device__ __forceinline__ float bf_hi(unsigned w) { return __uint_as_float(w & 0xffff0000u); }
; #define ATT_LOADK(t) do { rk0 = *(const u32x4*)(gk + (size_t)(64 * (t)) * NKN); rk1 = *(const u32x4*)(gk + (size_t)(64 * (t) + 32) * NKN); rr = *(const u32x4*)(gr + (size_t)(64 * (t)) * 64); } while (0)
; #define ATT_LOADV(t) do { rv0 = *(const u32x4*)(gv + 64 * (t)); rv1 = *(const u32x4*)(gv + (size_t)64 * M + 64 * (t)); } while (0)
; #define ATT_STOREK(ko) do { *(LAS u32x4*)(lds + (ko) + lk) = rk0; *(LAS u32x4*)(lds + (ko) + lk + 32 * KROW) = rk1; *(LAS u32x4*)(lds + (ko) + lr) = rr; } while (0)
; __device__ __forceinline__ void unit(LAS unsigned char* lds, int b, int h, int qb, const bf16_t* Q, const bf16_t* Kn, const bf16_t* Kr, const bf16_t* VT, const bf16_t* proj, bf16_t* ymix, int wv) {
;     ...
;     ATT_LOADK(0); ATT_LOADV(0); ATT_STOREK(0); ATT_STOREV(0);
;     ATT_LOADK(1); ATT_STOREK(KBUF);
;     __syncthreads();
; #pragma unroll
;     for (int ks = 0; ks < 12; ++ks) asm volatile("" : "+v"(qf[ks]));
;     int k0 = 0, k1 = KBUF, k2 = 2 * KBUF, v0 = 0, v1 = VBUF;
;     ...
;     lrun += shfl_xor_f(lrun, 32);
;     const float inv = 1.f / lrun;
;     const size_t tok = (size_t)tok0 + qidx;
;     u32x2 gts[4][4];
; #pragma unroll
;     for (int blk = 0; blk < 4; ++blk)
; #pragma unroll
;         for (int g = 0; g < 4; ++g) gts[blk][g] = *(const u32x2*)(proj + tok * NIN + PJ_BG + h * 128 + 32 * blk + 8 * g + 4 * hi);
; #pragma unroll
;     for (int blk = 0; blk < 4; ++blk)
; #pragma unroll
;         for (int g = 0; g < 4; ++g) { const int dv = 32 * blk + 8 * g + 4 * hi; const u32x2 gt = gts[blk][g];
;             u32x2 w; w.x = cvt_pk_bf16(o[blk][4 * g + 0] * inv * bf_lo(gt.x), o[blk][4 * g + 1] * inv * bf_hi(gt.x)); w.y = cvt_pk_bf16(o[blk][4 * g + 2] * inv * bf_lo(gt.y), o[blk][4 * g + 3] * inv * bf_hi(gt.y));
;             *(u32x2*)(ymix + tok * DM + 512 + h * 128 + dv) = w; }
.LBB0_1170:
	s_add_i32 s6, s58, 0
	s_add_i32 s6, s6, 0x12c00
	v_add3_u32 v0, s6, v227, v226
	ds_read2_b64 v[2:5], v0 offset1:2
	v_ashrrev_i32_e32 v217, 31, v216
	v_mov_b64_e32 v[6:7], s[46:47]
	v_lshl_add_u64 v[120:121], v[216:217], 0, s[16:17]
	v_mad_u64_u32 v[122:123], s[16:17], v120, s54, v[6:7]
	ds_read2_b64 v[6:9], v0 offset0:4 offset1:6
	ds_read2_b64 v[12:15], v0 offset0:8 offset1:10
	v_add_u32_e32 v88, 0x1000, v0
	v_add_u32_e32 v104, 0x2000, v0
	s_waitcnt lgkmcnt(2)
	v_mfma_f32_32x32x16_bf16 v[64:79], v[2:5], v[200:203], v[64:79]
	ds_read2_b64 v[2:5], v0 offset0:12 offset1:14
	v_add_u32_e32 v0, 0x3000, v0
	v_mad_i32_i24 v123, v121, s54, v123
	s_lshl_b32 s6, s56, 1
	ds_read2_b64 v[80:83], v88 offset0:32 offset1:34
	ds_read2_b64 v[84:87], v88 offset0:36 offset1:38
	v_mov_b32_e32 v11, v222
	s_add_i32 s3, s3, s31
	s_waitcnt lgkmcnt(4)
	v_mfma_f32_32x32x16_bf16 v[64:79], v[6:9], v[196:199], v[64:79]
	ds_read2_b64 v[6:9], v88 offset0:40 offset1:42
	ds_read2_b64 v[88:91], v88 offset0:44 offset1:46
	ds_read2_b64 v[92:95], v104 offset0:64 offset1:66
	ds_read2_b64 v[96:99], v104 offset0:68 offset1:70
	ds_read2_b64 v[100:103], v104 offset0:72 offset1:74
	ds_read2_b64 v[104:107], v104 offset0:76 offset1:78
	ds_read2_b64 v[108:111], v0 offset0:96 offset1:98
	s_cmpk_lt_i32 s3, 0x400
	s_waitcnt lgkmcnt(10)
	v_mfma_f32_32x32x16_bf16 v[64:79], v[12:15], v[192:195], v[64:79]
	ds_read2_b64 v[12:15], v0 offset0:100 offset1:102
	ds_read2_b64 v[112:115], v0 offset0:104 offset1:106
	ds_read2_b64 v[116:119], v0 offset0:108 offset1:110
	v_lshlrev_b32_e32 v0, 1, v225
	s_waitcnt lgkmcnt(0)
	s_barrier
	v_mfma_f32_32x32x16_bf16 v[64:79], v[2:5], v[188:191], v[64:79]
	v_lshl_add_u64 v[2:3], v[122:123], 0, s[6:7]
	v_lshl_add_u64 v[2:3], v[2:3], 0, v[0:1]
	v_add_co_u32_e32 v4, vcc, s55, v2
	s_nop 1
	v_addc_co_u32_e32 v5, vcc, 0, v3, vcc
	v_and_b32_e32 v168, 32, v222
	v_lshrrev_b32_e32 v168, 2, v168
	v_mov_b32_e32 v169, 0
	v_lshl_add_u64 v[168:169], v[4:5], 0, v[168:169]
	global_load_dwordx4 v[136:139], v[168:169], off
	v_lshl_add_u64 v[2:3], v[2:3], 0, s[10:11]
	v_mfma_f32_32x32x16_bf16 v[48:63], v[80:83], v[200:203], v[48:63]
	global_load_dwordx4 v[140:143], v[168:169], off offset:32
	v_lshlrev_b32_e32 v4, 2, v11
	v_xor_b32_e32 v4, 0x80, v4
	ds_bpermute_b32 v4, v4, v10
	v_mfma_f32_32x32x16_bf16 v[48:63], v[84:87], v[196:199], v[48:63]
	v_mfma_f32_32x32x16_bf16 v[48:63], v[6:9], v[192:195], v[48:63]
	s_waitcnt lgkmcnt(0)
	v_add_f32_e32 v6, v10, v4
	global_load_dwordx4 v[144:147], v[168:169], off offset:64
	global_load_dwordx4 v[148:151], v[168:169], off offset:96
	global_load_dwordx4 v[152:155], v[168:169], off offset:128
	v_div_scale_f32 v7, s[16:17], v6, v6, 1.0
	v_rcp_f32_e32 v134, v7
	v_mfma_f32_32x32x16_bf16 v[48:63], v[88:91], v[188:191], v[48:63]
	global_load_dwordx4 v[156:159], v[168:169], off offset:160
	global_load_dwordx4 v[160:163], v[168:169], off offset:192
	global_load_dwordx4 v[164:167], v[168:169], off offset:224
	s_nop 0
	v_mfma_f32_32x32x16_bf16 v[32:47], v[92:95], v[200:203], v[32:47]
	v_fma_f32 v92, -v7, v134, 1.0
	v_fmac_f32_e32 v134, v92, v134
	v_div_scale_f32 v92, vcc, 1.0, v6, 1.0
	v_mul_f32_e32 v93, v92, v134
	v_fma_f32 v94, -v7, v93, v92
	v_fmac_f32_e32 v93, v94, v134
	v_fma_f32 v7, -v7, v93, v92
	v_mfma_f32_32x32x16_bf16 v[16:31], v[108:111], v[200:203], v[16:31]
	v_div_fmas_f32 v7, v7, v134, v93
	v_div_fixup_f32 v92, v7, v6, 1.0
	v_mul_f32_e32 v64, v64, v92
	v_lshlrev_b64 v[6:7], 12, v[120:121]
	v_mul_f32_e32 v65, v65, v92
	v_lshl_add_u64 v[6:7], s[22:23], 0, v[6:7]
	v_lshl_add_u64 v[6:7], v[6:7], 0, s[6:7]
	v_lshl_add_u64 v[6:7], v[6:7], 0, v[0:1]
	v_mul_f32_e32 v0, v68, v92
	v_mfma_f32_32x32x16_bf16 v[16:31], v[12:15], v[196:199], v[16:31]
	v_mul_f32_e32 v12, v69, v92
	s_waitcnt vmcnt(7)
	v_permlane32_swap_b32_e32 v136, v138
	v_permlane32_swap_b32_e32 v137, v139
	v_lshlrev_b32_e32 v93, 16, v136
	v_mul_f32_e32 v64, v64, v93
	v_and_b32_e32 v93, 0xffff0000, v136
	v_mul_f32_e32 v65, v65, v93
	v_cvt_pk_bf16_f32 v244, v64, v65
	v_mul_f32_e32 v65, v66, v92
	v_lshlrev_b32_e32 v66, 16, v137
	v_mul_f32_e32 v65, v65, v66
	v_mul_f32_e32 v66, v67, v92
	v_and_b32_e32 v67, 0xffff0000, v137
	v_mul_f32_e32 v66, v66, v67
	v_cvt_pk_bf16_f32 v245, v65, v66
	v_and_b32_e32 v252, 32, v222
	v_lshrrev_b32_e32 v252, 2, v252
	v_mov_b32_e32 v253, 0
	v_lshl_add_u64 v[252:253], v[6:7], 0, v[252:253]
	s_waitcnt vmcnt(7)
	v_lshlrev_b32_e32 v64, 16, v138
	v_and_b32_e32 v13, 0xffff0000, v138
	v_mul_f32_e32 v0, v0, v64
	v_mul_f32_e32 v12, v12, v13
	v_cvt_pk_bf16_f32 v246, v0, v12
	v_mul_f32_e32 v0, v70, v92
	v_lshlrev_b32_e32 v13, 16, v139
	v_mul_f32_e32 v0, v0, v13
	v_mul_f32_e32 v13, v71, v92
	v_and_b32_e32 v14, 0xffff0000, v139
	v_mul_f32_e32 v13, v13, v14
	v_cvt_pk_bf16_f32 v247, v0, v13
	s_nop 1
	v_permlane32_swap_b32_e32 v244, v246
	v_permlane32_swap_b32_e32 v245, v247
	global_store_dwordx4 v[252:253], v[244:247], off offset:1024
	v_mul_f32_e32 v0, v72, v92
	s_waitcnt vmcnt(7)
	v_permlane32_swap_b32_e32 v140, v142
	v_permlane32_swap_b32_e32 v141, v143
	v_lshlrev_b32_e32 v12, 16, v140
	v_mul_f32_e32 v0, v0, v12
	v_mul_f32_e32 v12, v73, v92
	v_and_b32_e32 v13, 0xffff0000, v140
	v_mul_f32_e32 v12, v12, v13
	v_cvt_pk_bf16_f32 v248, v0, v12
	v_mul_f32_e32 v0, v74, v92
	v_lshlrev_b32_e32 v13, 16, v141
	v_mul_f32_e32 v0, v0, v13
	v_mul_f32_e32 v13, v75, v92
	v_and_b32_e32 v14, 0xffff0000, v141
	v_mul_f32_e32 v13, v13, v14
	v_cvt_pk_bf16_f32 v249, v0, v13
	v_mul_f32_e32 v0, v76, v92
	s_waitcnt vmcnt(7)
; __device__ __forceinline__ unsigned cvt_pk_bf16(float lo, float hi) { unsigned r; asm volatile("v_cvt_pk_bf16_f32 %0, %1, %2" : "=v"(r) : "v"(lo), "v"(hi)); return r; }
; __device__ __forceinline__ float bf_lo(unsigned w) { return __uint_as_float(w << 16); }
; __device__ __forceinline__ float bf_hi(unsigned w) { return __uint_as_float(w & 0xffff0000u); }
; __device__ __forceinline__ void unit(LAS unsigned char* lds, int b, int h, int qb, const bf16_t* Q, const bf16_t* Kn, const bf16_t* Kr, const bf16_t* VT, const bf16_t* proj, bf16_t* ymix, int wv) {
;     ...
;     u32x2 gts[4][4];
; #pragma unroll
;     for (int blk = 0; blk < 4; ++blk)
; #pragma unroll
;         for (int g = 0; g < 4; ++g) gts[blk][g] = *(const u32x2*)(proj + tok * NIN + PJ_BG + h * 128 + 32 * blk + 8 * g + 4 * hi);
; #pragma unroll
;     for (int blk = 0; blk < 4; ++blk)
; #pragma unroll
;         for (int g = 0; g < 4; ++g) { const int dv = 32 * blk + 8 * g + 4 * hi; const u32x2 gt = gts[blk][g];
;             u32x2 w; w.x = cvt_pk_bf16(o[blk][4 * g + 0] * inv * bf_lo(gt.x), o[blk][4 * g + 1] * inv * bf_hi(gt.x)); w.y = cvt_pk_bf16(o[blk][4 * g + 2] * inv * bf_lo(gt.y), o[blk][4 * g + 3] * inv * bf_hi(gt.y));
;             *(u32x2*)(ymix + tok * DM + 512 + h * 128 + dv) = w; }
	v_lshlrev_b32_e32 v12, 16, v142
	v_mul_f32_e32 v0, v0, v12
	v_mul_f32_e32 v12, v77, v92
	v_and_b32_e32 v10, 0xffff0000, v142
	v_mul_f32_e32 v10, v12, v10
	v_cvt_pk_bf16_f32 v250, v0, v10
	v_mul_f32_e32 v0, v78, v92
	v_lshlrev_b32_e32 v12, 16, v143
	v_mul_f32_e32 v0, v0, v12
	v_mul_f32_e32 v12, v79, v92
	v_and_b32_e32 v11, 0xffff0000, v143
	v_mul_f32_e32 v11, v12, v11
	v_mfma_f32_32x32x16_bf16 v[32:47], v[96:99], v[196:199], v[32:47]
	v_cvt_pk_bf16_f32 v251, v0, v11
	s_nop 1
	v_permlane32_swap_b32_e32 v248, v250
	v_permlane32_swap_b32_e32 v249, v251
	global_store_dwordx4 v[252:253], v[248:251], off offset:1056
	v_mul_f32_e32 v0, v48, v92
	s_waitcnt vmcnt(7)
	v_permlane32_swap_b32_e32 v144, v146
	v_permlane32_swap_b32_e32 v145, v147
	v_lshlrev_b32_e32 v10, 16, v144
	v_mul_f32_e32 v0, v0, v10
	v_mul_f32_e32 v10, v49, v92
	v_and_b32_e32 v11, 0xffff0000, v144
	v_mul_f32_e32 v10, v10, v11
	v_cvt_pk_bf16_f32 v244, v0, v10
	v_mul_f32_e32 v0, v50, v92
	v_lshlrev_b32_e32 v11, 16, v145
	v_mul_f32_e32 v0, v0, v11
	v_mul_f32_e32 v11, v51, v92
	v_and_b32_e32 v12, 0xffff0000, v145
	v_mul_f32_e32 v11, v11, v12
	v_cvt_pk_bf16_f32 v245, v0, v11
	v_mul_f32_e32 v0, v52, v92
	s_waitcnt vmcnt(7)
	v_lshlrev_b32_e32 v10, 16, v146
	v_mul_f32_e32 v0, v0, v10
	v_mul_f32_e32 v10, v53, v92
	v_and_b32_e32 v11, 0xffff0000, v146
	v_mfma_f32_32x32x16_bf16 v[32:47], v[100:103], v[192:195], v[32:47]
	v_mul_f32_e32 v10, v10, v11
	v_cvt_pk_bf16_f32 v246, v0, v10
	v_mul_f32_e32 v0, v54, v92
	v_lshlrev_b32_e32 v11, 16, v147
	v_mul_f32_e32 v0, v0, v11
	v_mul_f32_e32 v11, v55, v92
	v_and_b32_e32 v12, 0xffff0000, v147
	v_mul_f32_e32 v11, v11, v12
	v_cvt_pk_bf16_f32 v247, v0, v11
	s_nop 1
	v_permlane32_swap_b32_e32 v244, v246
	v_permlane32_swap_b32_e32 v245, v247
	global_store_dwordx4 v[252:253], v[244:247], off offset:1088
	v_mul_f32_e32 v0, v56, v92
	s_waitcnt vmcnt(7)
	v_permlane32_swap_b32_e32 v148, v150
	v_permlane32_swap_b32_e32 v149, v151
	v_lshlrev_b32_e32 v10, 16, v148
	v_mul_f32_e32 v0, v0, v10
	v_mul_f32_e32 v10, v57, v92
	v_and_b32_e32 v11, 0xffff0000, v148
	v_mul_f32_e32 v10, v10, v11
	v_cvt_pk_bf16_f32 v248, v0, v10
	v_mul_f32_e32 v0, v58, v92
	v_lshlrev_b32_e32 v11, 16, v149
	v_mfma_f32_32x32x16_bf16 v[32:47], v[104:107], v[188:191], v[32:47]
	v_mul_f32_e32 v0, v0, v11
	v_mul_f32_e32 v11, v59, v92
	v_and_b32_e32 v12, 0xffff0000, v149
	v_mul_f32_e32 v11, v11, v12
	v_cvt_pk_bf16_f32 v249, v0, v11
	v_mul_f32_e32 v0, v60, v92
	s_waitcnt vmcnt(7)
	v_lshlrev_b32_e32 v10, 16, v150
	v_mul_f32_e32 v0, v0, v10
	v_mul_f32_e32 v10, v61, v92
	v_and_b32_e32 v11, 0xffff0000, v150
	v_mul_f32_e32 v10, v10, v11
	v_cvt_pk_bf16_f32 v250, v0, v10
	v_mul_f32_e32 v0, v62, v92
	v_lshlrev_b32_e32 v11, 16, v151
	v_mul_f32_e32 v0, v0, v11
	v_mul_f32_e32 v11, v63, v92
	v_and_b32_e32 v12, 0xffff0000, v151
	v_mul_f32_e32 v11, v11, v12
	v_cvt_pk_bf16_f32 v251, v0, v11
	s_nop 1
	v_permlane32_swap_b32_e32 v248, v250
	v_permlane32_swap_b32_e32 v249, v251
	global_store_dwordx4 v[252:253], v[248:251], off offset:1120
	v_mul_f32_e32 v0, v32, v92
	s_waitcnt vmcnt(7)
	v_permlane32_swap_b32_e32 v152, v154
	v_permlane32_swap_b32_e32 v153, v155
	v_lshlrev_b32_e32 v10, 16, v152
	v_mul_f32_e32 v0, v0, v10
	v_mul_f32_e32 v10, v33, v92
	v_and_b32_e32 v11, 0xffff0000, v152
	v_mul_f32_e32 v10, v10, v11
	v_cvt_pk_bf16_f32 v244, v0, v10
	v_mul_f32_e32 v0, v34, v92
	v_lshlrev_b32_e32 v11, 16, v153
	v_mul_f32_e32 v0, v0, v11
	v_mul_f32_e32 v11, v35, v92
	v_and_b32_e32 v12, 0xffff0000, v153
	v_mul_f32_e32 v11, v11, v12
	v_cvt_pk_bf16_f32 v245, v0, v11
	v_mul_f32_e32 v0, v36, v92
	s_waitcnt vmcnt(7)
; __device__ __forceinline__ unsigned cvt_pk_bf16(float lo, float hi) { unsigned r; asm volatile("v_cvt_pk_bf16_f32 %0, %1, %2" : "=v"(r) : "v"(lo), "v"(hi)); return r; }
; __device__ __forceinline__ float bf_lo(unsigned w) { return __uint_as_float(w << 16); }
; __device__ __forceinline__ float bf_hi(unsigned w) { return __uint_as_float(w & 0xffff0000u); }
; __device__ __forceinline__ void unit(LAS unsigned char* lds, int b, int h, int qb, const bf16_t* Q, const bf16_t* Kn, const bf16_t* Kr, const bf16_t* VT, const bf16_t* proj, bf16_t* ymix, int wv) {
;     ...
; #pragma unroll
;     for (int blk = 0; blk < 4; ++blk)
; #pragma unroll
;         for (int g = 0; g < 4; ++g) gts[blk][g] = *(const u32x2*)(proj + tok * NIN + PJ_BG + h * 128 + 32 * blk + 8 * g + 4 * hi);
; #pragma unroll
;     for (int blk = 0; blk < 4; ++blk)
; #pragma unroll
;         for (int g = 0; g < 4; ++g) { const int dv = 32 * blk + 8 * g + 4 * hi; const u32x2 gt = gts[blk][g];
;             u32x2 w; w.x = cvt_pk_bf16(o[blk][4 * g + 0] * inv * bf_lo(gt.x), o[blk][4 * g + 1] * inv * bf_hi(gt.x)); w.y = cvt_pk_bf16(o[blk][4 * g + 2] * inv * bf_lo(gt.y), o[blk][4 * g + 3] * inv * bf_hi(gt.y));
;             *(u32x2*)(ymix + tok * DM + 512 + h * 128 + dv) = w; }
	v_lshlrev_b32_e32 v10, 16, v154
	v_mul_f32_e32 v0, v0, v10
	v_mul_f32_e32 v10, v37, v92
	v_and_b32_e32 v11, 0xffff0000, v154
	v_mfma_f32_32x32x16_bf16 v[16:31], v[112:115], v[192:195], v[16:31]
	v_mul_f32_e32 v10, v10, v11
	v_cvt_pk_bf16_f32 v246, v0, v10
	v_mul_f32_e32 v0, v38, v92
	v_lshlrev_b32_e32 v11, 16, v155
	v_mul_f32_e32 v0, v0, v11
	v_mul_f32_e32 v11, v39, v92
	v_and_b32_e32 v12, 0xffff0000, v155
	v_mul_f32_e32 v11, v11, v12
	v_cvt_pk_bf16_f32 v247, v0, v11
	s_nop 1
	v_permlane32_swap_b32_e32 v244, v246
	v_permlane32_swap_b32_e32 v245, v247
	global_store_dwordx4 v[252:253], v[244:247], off offset:1152
	v_mul_f32_e32 v0, v40, v92
	s_waitcnt vmcnt(7)
	v_permlane32_swap_b32_e32 v156, v158
	v_permlane32_swap_b32_e32 v157, v159
	v_lshlrev_b32_e32 v10, 16, v156
	v_mul_f32_e32 v0, v0, v10
	v_mul_f32_e32 v10, v41, v92
	v_and_b32_e32 v11, 0xffff0000, v156
	v_mul_f32_e32 v10, v10, v11
	v_cvt_pk_bf16_f32 v248, v0, v10
	v_mul_f32_e32 v0, v42, v92
	v_lshlrev_b32_e32 v11, 16, v157
	v_mfma_f32_32x32x16_bf16 v[16:31], v[116:119], v[188:191], v[16:31]
	v_mul_f32_e32 v0, v0, v11
	v_mul_f32_e32 v11, v43, v92
	v_and_b32_e32 v12, 0xffff0000, v157
	v_mul_f32_e32 v11, v11, v12
	v_cvt_pk_bf16_f32 v249, v0, v11
	v_mul_f32_e32 v0, v44, v92
	s_waitcnt vmcnt(7)
	v_lshlrev_b32_e32 v10, 16, v158
	v_mul_f32_e32 v0, v0, v10
	v_mul_f32_e32 v10, v45, v92
	v_and_b32_e32 v11, 0xffff0000, v158
	v_mul_f32_e32 v10, v10, v11
	v_cvt_pk_bf16_f32 v250, v0, v10
	v_mul_f32_e32 v0, v46, v92
	v_lshlrev_b32_e32 v11, 16, v159
	v_mul_f32_e32 v0, v0, v11
	v_mul_f32_e32 v11, v47, v92
	v_and_b32_e32 v12, 0xffff0000, v159
	v_mul_f32_e32 v11, v11, v12
	v_cvt_pk_bf16_f32 v251, v0, v11
	s_nop 1
	v_permlane32_swap_b32_e32 v248, v250
	v_permlane32_swap_b32_e32 v249, v251
	global_store_dwordx4 v[252:253], v[248:251], off offset:1184
	v_mul_f32_e32 v0, v16, v92
	s_waitcnt vmcnt(7)
	v_permlane32_swap_b32_e32 v160, v162
	v_permlane32_swap_b32_e32 v161, v163
	v_lshlrev_b32_e32 v10, 16, v160
	v_mul_f32_e32 v0, v0, v10
	v_mul_f32_e32 v10, v17, v92
	v_and_b32_e32 v11, 0xffff0000, v160
	v_mul_f32_e32 v10, v10, v11
	v_cvt_pk_bf16_f32 v244, v0, v10
	v_mul_f32_e32 v0, v18, v92
	v_lshlrev_b32_e32 v11, 16, v161
	v_mul_f32_e32 v0, v0, v11
	v_mul_f32_e32 v11, v19, v92
	v_and_b32_e32 v12, 0xffff0000, v161
	v_mul_f32_e32 v11, v11, v12
	v_cvt_pk_bf16_f32 v245, v0, v11
	v_mul_f32_e32 v0, v20, v92
	s_waitcnt vmcnt(7)
	v_lshlrev_b32_e32 v10, 16, v162
	v_mul_f32_e32 v0, v0, v10
	v_mul_f32_e32 v10, v21, v92
	v_and_b32_e32 v8, 0xffff0000, v162
	v_mul_f32_e32 v8, v10, v8
	v_cvt_pk_bf16_f32 v246, v0, v8
	v_mul_f32_e32 v0, v22, v92
	v_lshlrev_b32_e32 v10, 16, v163
	v_mul_f32_e32 v0, v0, v10
	v_mul_f32_e32 v10, v23, v92
	v_and_b32_e32 v9, 0xffff0000, v163
	v_mul_f32_e32 v9, v10, v9
	v_cvt_pk_bf16_f32 v247, v0, v9
	s_nop 1
	v_permlane32_swap_b32_e32 v244, v246
	v_permlane32_swap_b32_e32 v245, v247
	global_store_dwordx4 v[252:253], v[244:247], off offset:1216
	v_mul_f32_e32 v0, v24, v92
	s_waitcnt vmcnt(7)
	v_permlane32_swap_b32_e32 v164, v166
	v_permlane32_swap_b32_e32 v165, v167
	v_lshlrev_b32_e32 v8, 16, v164
	v_mul_f32_e32 v0, v0, v8
	v_mul_f32_e32 v8, v25, v92
	v_and_b32_e32 v4, 0xffff0000, v164
	v_mul_f32_e32 v4, v8, v4
	v_cvt_pk_bf16_f32 v248, v0, v4
	v_mul_f32_e32 v0, v26, v92
	v_lshlrev_b32_e32 v8, 16, v165
	v_mul_f32_e32 v0, v0, v8
	v_mul_f32_e32 v8, v27, v92
	v_and_b32_e32 v5, 0xffff0000, v165
	v_mul_f32_e32 v5, v8, v5
	v_cvt_pk_bf16_f32 v249, v0, v5
	v_mul_f32_e32 v0, v28, v92
	s_waitcnt vmcnt(7)
	v_lshlrev_b32_e32 v4, 16, v166
	v_mul_f32_e32 v0, v0, v4
	v_mul_f32_e32 v4, v29, v92
	v_and_b32_e32 v2, 0xffff0000, v166
	v_mul_f32_e32 v2, v4, v2
	v_cvt_pk_bf16_f32 v250, v0, v2
	v_mul_f32_e32 v0, v30, v92
	v_lshlrev_b32_e32 v4, 16, v167
	v_mul_f32_e32 v0, v0, v4
	v_mul_f32_e32 v4, v31, v92
	v_and_b32_e32 v3, 0xffff0000, v167
	v_mul_f32_e32 v3, v4, v3
	v_cvt_pk_bf16_f32 v251, v0, v3
	s_nop 1
	v_permlane32_swap_b32_e32 v248, v250
	v_permlane32_swap_b32_e32 v249, v251
	global_store_dwordx4 v[252:253], v[248:251], off offset:1248
	s_cbranch_scc0 .LBB0_1198
